# GLA step b: four token groups processed together with exact logsig range-check removal; GLA setup loads and token0 norm-weight loads issued together
# speedup vs baseline: 1.0090x; 1.0050x over previous
; #define LAS __attribute__((address_space(3)))
; DI bf16_t f2bf(float f) { return (bf16_t)(cvt_pk_bf16(f, 0.f) & 0xffffu); }
; DI void gla_item(ldsp lds, const Params& p, const bf16_t* proj, bf16_t* obuf, const float* q0k0, int jl, int item, int tid, int wid, int lane) {
;     ...
;         float wv6[6];
; #pragma unroll
;         for (int i = 0; i < 6; ++i) { const int e = tid + i * 512, d = e >> 5, kk = e & 31;
;             wv6[i] = kk < 16 ? p.w_gate_up[(size_t)(jl * 16 + kk) * 384 + h * 96 + d] : 0.f; }
; #pragma unroll
;         for (int i = 0; i < 6; ++i) { const int e = tid + i * 512, d = e >> 5, kk = e & 31; *(LAS bf16_t*)(WG + d * SGL + kk * 2) = f2bf(wv6[i]); }
.LBB0_452:
	s_bfe_u32 s93, s19, 0x20001
	s_mul_i32 s94, s93, 0x60
	s_lshl_b32 s0, s94, 2
	s_waitcnt vmcnt(2)
	v_lshl_add_u64 v[0:1], v[70:71], 0, s[0:1]
	v_mov_b32_e32 v2, 0
	v_mov_b32_e32 v3, 0
	v_mov_b32_e32 v4, 0
	v_mov_b32_e32 v5, 0
	v_mov_b32_e32 v6, 0
	v_mov_b32_e32 v7, 0
	s_waitcnt vmcnt(0)
	s_and_saveexec_b64 s[22:23], s[38:39]
	s_cbranch_execz .LBB0_464
	v_lshl_add_u64 v[224:225], v[72:73], 2, v[0:1]
	v_lshl_add_u64 v[226:227], v[74:75], 2, v[0:1]
	v_lshl_add_u64 v[228:229], v[76:77], 2, v[0:1]
	v_lshl_add_u64 v[242:243], v[78:79], 2, v[0:1]
	v_lshl_add_u64 v[244:245], v[80:81], 2, v[0:1]
	v_lshl_add_u64 v[246:247], v[82:83], 2, v[0:1]
	global_load_dword v3, v[224:225], off
	global_load_dword v2, v[226:227], off
	global_load_dword v5, v[228:229], off
	global_load_dword v4, v[242:243], off
	global_load_dword v7, v[244:245], off
	global_load_dword v6, v[246:247], off
	s_waitcnt vmcnt(0)
	v_cvt_pk_bf16_f32 v3, v3, s0
	v_cvt_pk_bf16_f32 v2, v2, s0
	v_cvt_pk_bf16_f32 v5, v5, s0
	v_cvt_pk_bf16_f32 v4, v4, s0
	v_cvt_pk_bf16_f32 v7, v7, s0
	v_cvt_pk_bf16_f32 v6, v6, s0

; #define LAS __attribute__((address_space(3)))
; DI f32x4 mfma16(bf16x8 a, bf16x8 b, f32x4 c) { return __builtin_amdgcn_mfma_f32_16x16x32_bf16(a, b, c, 0, 0, 0); }
; DI float logsig_f(float x) { return fminf(x, 0.f) - __logf(1.0f + __expf(-fabsf(x))); }
; DI void gla_item(ldsp lds, const Params& p, const bf16_t* proj, bf16_t* obuf, const float* q0k0, int jl, int item, int tid, int wid, int lane) {
;     ...
;         *(LAS u32x4*)(Vl + row0 * S96 + ch0 * 16) = vreg0;
;         if (has1) *(LAS u32x4*)(Vl + row1 * S96 + ch1 * 16) = vreg1;
;         if (tid < 128) *(LAS u32x4*)(GL + (tid >> 1) * SGL + (tid & 1) * 16) = greg;
;         __syncthreads();
;         if (wid < 6) {
;             const int d = 16 * wid + li; const float bias = BG[d];
;             const bf16x8 bb = lds_rd8(WG + (16 * wid + li) * SGL + quad * 16);
;             float base = 0.f;
; #pragma unroll
;             for (int it = 0; it < 4; ++it) {
;                 const bf16x8 a = lds_rd8(GL + (16 * it + li) * SGL + quad * 16);
;                 const f32x4 c = mfma16(a, bb, (f32x4){0.f, 0.f, 0.f, 0.f});
;                 const float c0 = logsig_f(c[0] + bias) * (1.0f / 16.0f);
;                 const float c1 = c0 + logsig_f(c[1] + bias) * (1.0f / 16.0f);
;                 const float c2 = c1 + logsig_f(c[2] + bias) * (1.0f / 16.0f);
;                 const float c3 = c2 + logsig_f(c[3] + bias) * (1.0f / 16.0f);
.LBB0_484:
	s_waitcnt vmcnt(0)
	ds_write_b128 v178, v[8:11]
	s_and_saveexec_b64 s[22:23], s[46:47]
	ds_write_b128 v179, v[24:27]
	s_or_b64 exec, exec, s[22:23]
	s_and_saveexec_b64 s[22:23], s[48:49]
	ds_write_b128 v198, v[28:31]
	s_or_b64 exec, exec, s[22:23]
	v_cndmask_b32_e64 v13, 0, 1, s[36:37]
	v_cmp_ne_u32_e64 s[74:75], 1, v13
	s_andn2_b64 vcc, exec, s[36:37]
	s_waitcnt lgkmcnt(0)
	s_barrier
	s_cbranch_vccnz .LBB0_490
	v_add_u32_e32 v14, v94, v69
	ds_read_b32 v13, v92 offset:12800
	ds_read_b128 v[60:63], v14 offset:5120
	ds_read_b128 v[64:67], v180
	ds_read_b128 v[200:203], v180 offset:1280
	ds_read_b128 v[204:207], v180 offset:2560
	ds_read_b128 v[208:211], v182
	s_waitcnt lgkmcnt(0)
	v_mfma_f32_16x16x32_bf16 v[64:67], v[64:67], v[60:63], 0
	v_mfma_f32_16x16x32_bf16 v[200:203], v[200:203], v[60:63], 0
	v_mfma_f32_16x16x32_bf16 v[204:207], v[204:207], v[60:63], 0
	v_mfma_f32_16x16x32_bf16 v[208:211], v[208:211], v[60:63], 0
	s_nop 4
	v_add_f32_e32 v64, v13, v64
	v_add_f32_e32 v65, v13, v65
	v_add_f32_e32 v66, v13, v66
	v_add_f32_e32 v67, v13, v67
	v_add_f32_e32 v200, v13, v200
	v_add_f32_e32 v201, v13, v201
	v_add_f32_e32 v202, v13, v202
	v_add_f32_e32 v203, v13, v203
	v_min_f32_e32 v212, 0, v64
	v_min_f32_e32 v213, 0, v65
	v_min_f32_e32 v214, 0, v66
	v_min_f32_e32 v215, 0, v67
	v_min_f32_e32 v216, 0, v200
	v_min_f32_e32 v217, 0, v201
	v_min_f32_e32 v218, 0, v202
	v_min_f32_e32 v219, 0, v203
	v_mul_f32_e64 v64, |v64|, s89
	v_mul_f32_e64 v65, |v65|, s89
	v_mul_f32_e64 v66, |v66|, s89
	v_mul_f32_e64 v67, |v67|, s89
	v_mul_f32_e64 v200, |v200|, s89
	v_mul_f32_e64 v201, |v201|, s89
	v_mul_f32_e64 v202, |v202|, s89
	v_mul_f32_e64 v203, |v203|, s89
	v_exp_f32_e32 v64, v64
	v_exp_f32_e32 v65, v65
	v_exp_f32_e32 v66, v66
	v_exp_f32_e32 v67, v67
	v_exp_f32_e32 v200, v200
	v_exp_f32_e32 v201, v201
	v_exp_f32_e32 v202, v202
	v_exp_f32_e32 v203, v203
	v_add_f32_e32 v64, 1.0, v64
	v_add_f32_e32 v65, 1.0, v65
	v_add_f32_e32 v66, 1.0, v66
	v_add_f32_e32 v67, 1.0, v67
	v_add_f32_e32 v200, 1.0, v200
	v_add_f32_e32 v201, 1.0, v201
	v_add_f32_e32 v202, 1.0, v202
	v_add_f32_e32 v203, 1.0, v203
	v_log_f32_e32 v64, v64
	v_log_f32_e32 v65, v65
	v_log_f32_e32 v66, v66
	v_log_f32_e32 v67, v67
	v_log_f32_e32 v200, v200
	v_log_f32_e32 v201, v201
	v_log_f32_e32 v202, v202
	v_log_f32_e32 v203, v203
	v_mul_f32_e32 v220, 0x3f317217, v64
	v_mul_f32_e32 v221, 0x3f317217, v65
	v_mul_f32_e32 v222, 0x3f317217, v66
	v_mul_f32_e32 v223, 0x3f317217, v67
	v_mul_f32_e32 v224, 0x3f317217, v200
	v_mul_f32_e32 v225, 0x3f317217, v201
	v_mul_f32_e32 v226, 0x3f317217, v202
	v_mul_f32_e32 v227, 0x3f317217, v203
	v_fma_f32 v220, v64, s84, -v220
	v_fma_f32 v221, v65, s84, -v221
	v_fma_f32 v222, v66, s84, -v222
	v_fma_f32 v223, v67, s84, -v223
	v_fma_f32 v224, v200, s84, -v224
	v_fma_f32 v225, v201, s84, -v225
	v_fma_f32 v226, v202, s84, -v226
	v_fma_f32 v227, v203, s84, -v227
	v_fmac_f32_e32 v220, 0x3377d1cf, v64
	v_fmac_f32_e32 v221, 0x3377d1cf, v65
	v_fmac_f32_e32 v222, 0x3377d1cf, v66
	v_fmac_f32_e32 v223, 0x3377d1cf, v67
	v_fmac_f32_e32 v224, 0x3377d1cf, v200
	v_fmac_f32_e32 v225, 0x3377d1cf, v201
	v_fmac_f32_e32 v226, 0x3377d1cf, v202
	v_fmac_f32_e32 v227, 0x3377d1cf, v203
	v_fmac_f32_e32 v220, 0x3f317217, v64
	v_fmac_f32_e32 v221, 0x3f317217, v65
	v_fmac_f32_e32 v222, 0x3f317217, v66
	v_fmac_f32_e32 v223, 0x3f317217, v67
	v_fmac_f32_e32 v224, 0x3f317217, v200
	v_fmac_f32_e32 v225, 0x3f317217, v201
	v_fmac_f32_e32 v226, 0x3f317217, v202
	v_fmac_f32_e32 v227, 0x3f317217, v203
	v_sub_f32_e32 v64, v212, v220
	v_sub_f32_e32 v65, v213, v221
	v_sub_f32_e32 v66, v214, v222
	v_sub_f32_e32 v67, v215, v223
	v_sub_f32_e32 v200, v216, v224
	v_sub_f32_e32 v201, v217, v225
	v_sub_f32_e32 v202, v218, v226
	v_sub_f32_e32 v203, v219, v227
	v_add_f32_e32 v204, v13, v204
	v_add_f32_e32 v205, v13, v205
	v_add_f32_e32 v206, v13, v206
	v_add_f32_e32 v207, v13, v207
	v_add_f32_e32 v208, v13, v208
	v_add_f32_e32 v209, v13, v209
	v_add_f32_e32 v210, v13, v210
	v_add_f32_e32 v211, v13, v211
	v_min_f32_e32 v212, 0, v204
	v_min_f32_e32 v213, 0, v205
	v_min_f32_e32 v214, 0, v206
	v_min_f32_e32 v215, 0, v207
	v_min_f32_e32 v216, 0, v208
	v_min_f32_e32 v217, 0, v209
	v_min_f32_e32 v218, 0, v210
	v_min_f32_e32 v219, 0, v211
	v_mul_f32_e64 v204, |v204|, s89
	v_mul_f32_e64 v205, |v205|, s89
	v_mul_f32_e64 v206, |v206|, s89
	v_mul_f32_e64 v207, |v207|, s89
	v_mul_f32_e64 v208, |v208|, s89
	v_mul_f32_e64 v209, |v209|, s89
	v_mul_f32_e64 v210, |v210|, s89
	v_mul_f32_e64 v211, |v211|, s89
	v_exp_f32_e32 v204, v204
	v_exp_f32_e32 v205, v205
	v_exp_f32_e32 v206, v206
	v_exp_f32_e32 v207, v207
	v_exp_f32_e32 v208, v208
	v_exp_f32_e32 v209, v209
	v_exp_f32_e32 v210, v210
	v_exp_f32_e32 v211, v211
	v_add_f32_e32 v204, 1.0, v204
	v_add_f32_e32 v205, 1.0, v205
	v_add_f32_e32 v206, 1.0, v206
	v_add_f32_e32 v207, 1.0, v207
	v_add_f32_e32 v208, 1.0, v208
	v_add_f32_e32 v209, 1.0, v209
	v_add_f32_e32 v210, 1.0, v210
	v_add_f32_e32 v211, 1.0, v211
	v_log_f32_e32 v204, v204
	v_log_f32_e32 v205, v205
	v_log_f32_e32 v206, v206
	v_log_f32_e32 v207, v207
	v_log_f32_e32 v208, v208
	v_log_f32_e32 v209, v209
	v_log_f32_e32 v210, v210
	v_log_f32_e32 v211, v211
	v_mul_f32_e32 v220, 0x3f317217, v204
; #define LAS __attribute__((address_space(3)))
; DI unsigned cvt_pk_bf16(float lo, float hi) { const f32x2_t v = {lo, hi}; const bf16v2_t b = __builtin_convertvector(v, bf16v2_t); return __builtin_bit_cast(unsigned, b); }
; DI float logsig_f(float x) { return fminf(x, 0.f) - __logf(1.0f + __expf(-fabsf(x))); }
; DI void gla_item(ldsp lds, const Params& p, const bf16_t* proj, bf16_t* obuf, const float* q0k0, int jl, int item, int tid, int wid, int lane) {
;     ...
;                 const float c0 = logsig_f(c[0] + bias) * (1.0f / 16.0f);
;                 const float c1 = c0 + logsig_f(c[1] + bias) * (1.0f / 16.0f);
;                 const float c2 = c1 + logsig_f(c[2] + bias) * (1.0f / 16.0f);
;                 const float c3 = c2 + logsig_f(c[3] + bias) * (1.0f / 16.0f);
;                 float sc = c3;
;                 float t = __shfl_up(sc, 16); if (quad >= 1) sc += t;
;                 t = __shfl_up(sc, 32); if (quad >= 2) sc += t;
;                 const float tot = __shfl(sc, 48 + li);
;                 const float o = base + (sc - c3);
;                 LAS float* lp = LA + (16 * it + quad * 4) * SLA + d;
;                 lp[0] = o + c0; lp[SLA] = o + c1; lp[2 * SLA] = o + c2; lp[3 * SLA] = o + c3;
;                 base += tot;
;             }
; #pragma unroll
;             for (int dt = 0; dt < 6; ++dt) { u32x2 w; w.x = cvt_pk_bf16(S[dt][0], S[dt][1]); w.y = cvt_pk_bf16(S[dt][2], S[dt][3]);
;                 *(LAS u32x2*)(ST + (16 * wid + li) * S96 + (16 * dt + quad * 4) * 2) = w; }
	v_mul_f32_e32 v221, 0x3f317217, v205
	v_mul_f32_e32 v222, 0x3f317217, v206
	v_mul_f32_e32 v223, 0x3f317217, v207
	v_mul_f32_e32 v224, 0x3f317217, v208
	v_mul_f32_e32 v225, 0x3f317217, v209
	v_mul_f32_e32 v226, 0x3f317217, v210
	v_mul_f32_e32 v227, 0x3f317217, v211
	v_fma_f32 v220, v204, s84, -v220
	v_fma_f32 v221, v205, s84, -v221
	v_fma_f32 v222, v206, s84, -v222
	v_fma_f32 v223, v207, s84, -v223
	v_fma_f32 v224, v208, s84, -v224
	v_fma_f32 v225, v209, s84, -v225
	v_fma_f32 v226, v210, s84, -v226
	v_fma_f32 v227, v211, s84, -v227
	v_fmac_f32_e32 v220, 0x3377d1cf, v204
	v_fmac_f32_e32 v221, 0x3377d1cf, v205
	v_fmac_f32_e32 v222, 0x3377d1cf, v206
	v_fmac_f32_e32 v223, 0x3377d1cf, v207
	v_fmac_f32_e32 v224, 0x3377d1cf, v208
	v_fmac_f32_e32 v225, 0x3377d1cf, v209
	v_fmac_f32_e32 v226, 0x3377d1cf, v210
	v_fmac_f32_e32 v227, 0x3377d1cf, v211
	v_fmac_f32_e32 v220, 0x3f317217, v204
	v_fmac_f32_e32 v221, 0x3f317217, v205
	v_fmac_f32_e32 v222, 0x3f317217, v206
	v_fmac_f32_e32 v223, 0x3f317217, v207
	v_fmac_f32_e32 v224, 0x3f317217, v208
	v_fmac_f32_e32 v225, 0x3f317217, v209
	v_fmac_f32_e32 v226, 0x3f317217, v210
	v_fmac_f32_e32 v227, 0x3f317217, v211
	v_sub_f32_e32 v204, v212, v220
	v_sub_f32_e32 v205, v213, v221
	v_sub_f32_e32 v206, v214, v222
	v_sub_f32_e32 v207, v215, v223
	v_sub_f32_e32 v208, v216, v224
	v_sub_f32_e32 v209, v217, v225
	v_sub_f32_e32 v210, v218, v226
	v_sub_f32_e32 v211, v219, v227
	v_mul_f32_e32 v212, 0x3d800000, v65
	v_mul_f32_e32 v213, 0x3d800000, v201
	v_mul_f32_e32 v214, 0x3d800000, v205
	v_mul_f32_e32 v215, 0x3d800000, v209
	v_fmac_f32_e32 v212, 0x3d800000, v64
	v_fmac_f32_e32 v213, 0x3d800000, v200
	v_fmac_f32_e32 v214, 0x3d800000, v204
	v_fmac_f32_e32 v215, 0x3d800000, v208
	v_fmamk_f32 v216, v66, 0x3d800000, v212
	v_fmamk_f32 v217, v202, 0x3d800000, v213
	v_fmamk_f32 v218, v206, 0x3d800000, v214
	v_fmamk_f32 v219, v210, 0x3d800000, v215
	v_fmamk_f32 v220, v67, 0x3d800000, v216
	v_fmamk_f32 v221, v203, 0x3d800000, v217
	v_fmamk_f32 v222, v207, 0x3d800000, v218
	v_fmamk_f32 v223, v211, 0x3d800000, v219
	ds_bpermute_b32 v224, v95, v220
	ds_bpermute_b32 v225, v95, v221
	ds_bpermute_b32 v226, v95, v222
	ds_bpermute_b32 v227, v95, v223
	s_waitcnt lgkmcnt(0)
	v_add_f32_e32 v224, v220, v224
	v_add_f32_e32 v225, v221, v225
	v_add_f32_e32 v226, v222, v226
	v_add_f32_e32 v227, v223, v227
	v_cndmask_b32_e64 v228, v224, v220, s[50:51]
	v_cndmask_b32_e64 v229, v225, v221, s[50:51]
	v_cndmask_b32_e64 v230, v226, v222, s[50:51]
	v_cndmask_b32_e64 v232, v227, v223, s[50:51]
	ds_bpermute_b32 v224, v163, v228
	ds_bpermute_b32 v225, v163, v229
	ds_bpermute_b32 v226, v163, v230
	ds_bpermute_b32 v227, v163, v232
	s_waitcnt lgkmcnt(0)
	v_add_f32_e32 v224, v228, v224
	v_add_f32_e32 v225, v229, v225
	v_add_f32_e32 v226, v230, v226
	v_add_f32_e32 v227, v232, v227
	v_cndmask_b32_e64 v228, v228, v224, s[52:53]
	v_cndmask_b32_e64 v229, v229, v225, s[52:53]
	v_cndmask_b32_e64 v230, v230, v226, s[52:53]
	v_cndmask_b32_e64 v232, v232, v227, s[52:53]
	ds_bpermute_b32 v224, v164, v228
	ds_bpermute_b32 v225, v164, v229
	ds_bpermute_b32 v226, v164, v230
	v_sub_f32_e32 v242, v228, v220
	v_sub_f32_e32 v243, v229, v221
	v_sub_f32_e32 v244, v230, v222
	v_sub_f32_e32 v245, v232, v223
	v_add_f32_e32 v246, 0, v242
	s_waitcnt lgkmcnt(0)
	v_add_f32_e32 v250, 0, v224
	v_add_f32_e32 v247, v250, v243
	v_add_f32_e32 v250, v250, v225
	v_add_f32_e32 v248, v250, v244
	v_add_f32_e32 v250, v250, v226
	v_add_f32_e32 v249, v250, v245
	v_add_u32_e32 v160, 0x3400, v181
	v_fmamk_f32 v14, v64, 0x3d800000, v246
	v_add_f32_e32 v15, v212, v246
	ds_write2_b32 v160, v14, v15 offset1:100
	v_add_u32_e32 v161, 0x3720, v181
	v_add_f32_e32 v158, v216, v246
	v_add_f32_e32 v159, v220, v246
	ds_write2_b32 v161, v158, v159 offset1:100
	v_add_u32_e32 v160, 0x4d00, v181
	v_fmamk_f32 v14, v200, 0x3d800000, v247
	v_add_f32_e32 v15, v213, v247
	ds_write2_b32 v160, v14, v15 offset1:100
	v_add_u32_e32 v161, 0x5020, v181
	v_add_f32_e32 v158, v217, v247
	v_add_f32_e32 v159, v221, v247
	ds_write2_b32 v161, v158, v159 offset1:100
	v_add_u32_e32 v160, 0x6600, v181
	v_fmamk_f32 v14, v204, 0x3d800000, v248
	v_add_f32_e32 v15, v214, v248
	ds_write2_b32 v160, v14, v15 offset1:100
	v_add_u32_e32 v161, 0x6920, v181
	v_add_f32_e32 v158, v218, v248
	v_add_f32_e32 v159, v222, v248
	ds_write2_b32 v161, v158, v159 offset1:100
	v_add_u32_e32 v160, 0x7f00, v181
	v_fmamk_f32 v14, v208, 0x3d800000, v249
	v_add_f32_e32 v15, v215, v249
	ds_write2_b32 v160, v14, v15 offset1:100
	v_add_u32_e32 v161, 0x8220, v181
	v_add_f32_e32 v158, v219, v249
	v_add_f32_e32 v159, v223, v249
	ds_write2_b32 v161, v158, v159 offset1:100
	v_cvt_pk_bf16_f32 v14, v40, v41
	v_cvt_pk_bf16_f32 v15, v42, v43
	v_add_u32_e32 v13, v165, v68
	v_cvt_pk_bf16_f32 v60, v52, v53
	v_cvt_pk_bf16_f32 v61, v54, v55
	ds_write2_b64 v13, v[14:15], v[60:61] offset1:4
	v_cvt_pk_bf16_f32 v14, v48, v49
	v_cvt_pk_bf16_f32 v15, v50, v51
	v_cvt_pk_bf16_f32 v60, v36, v37
	v_cvt_pk_bf16_f32 v61, v38, v39
	ds_write2_b64 v13, v[14:15], v[60:61] offset0:8 offset1:12
	v_cvt_pk_bf16_f32 v14, v44, v45
	v_cvt_pk_bf16_f32 v15, v46, v47
	v_cvt_pk_bf16_f32 v60, v56, v57
	v_cvt_pk_bf16_f32 v61, v58, v59
	ds_write2_b64 v13, v[14:15], v[60:61] offset0:16 offset1:20

; DI void token0_task(ldsp lds, const float* xcur, size_t xstride, const float* nw, const float* win, float* q0k0, int task, int tid, int wid, int lane) {
;     ...
;     const float* xr = xcur + (size_t)b * xstride;
;     const float v0 = xr[tid], v1 = xr[tid + 512];
;     const float sq = wave_sum(v0 * v0 + v1 * v1);
;     if (lane == 0) RED[wid] = sq;
;     __syncthreads();
;     float tot = 0.f;
; #pragma unroll
;     for (int i = 0; i < 8; ++i) tot += RED[i];
;     const float rs = rsqrtf(tot * (1.0f / 1024.0f) + 1e-6f);
;     HX[tid] = v0 * rs * nw[tid]; HX[tid + 512] = v1 * rs * nw[tid + 512];
.LBB0_811:
	s_ashr_i32 s14, s23, 3
	s_ashr_i32 s15, s14, 31
	s_lshl_b64 s[18:19], s[14:15], s17
	v_lshl_add_u64 v[2:3], s[18:19], 2, v[8:9]
	global_load_dword v0, v[2:3], off offset:2048
	global_load_dword v1, v[2:3], off
	global_load_dword v224, v[4:5], off
	global_load_dword v225, v[4:5], off offset:2048
	s_waitcnt vmcnt(3)
	v_mul_f32_e32 v2, v0, v0
	s_waitcnt vmcnt(2)
	v_fmac_f32_e32 v2, v1, v1
	ds_bpermute_b32 v3, v16, v2
	s_waitcnt lgkmcnt(0)
	v_add_f32_e32 v2, v2, v3
	ds_bpermute_b32 v3, v17, v2
	s_waitcnt lgkmcnt(0)
	v_add_f32_e32 v2, v2, v3
	ds_bpermute_b32 v3, v18, v2
	s_waitcnt lgkmcnt(0)
	v_add_f32_e32 v2, v2, v3
	ds_bpermute_b32 v3, v19, v2
	s_waitcnt lgkmcnt(0)
	v_add_f32_e32 v2, v2, v3
	ds_bpermute_b32 v3, v20, v2
	s_waitcnt lgkmcnt(0)
	v_add_f32_e32 v2, v2, v3
	ds_bpermute_b32 v3, v21, v2
	s_and_saveexec_b64 s[18:19], s[38:39]
	s_cbranch_execz .LBB0_813
	s_waitcnt lgkmcnt(0)
	v_add_f32_e32 v2, v2, v3
	v_mov_b32_e32 v3, s22
	ds_write_b32 v3, v2 offset:12160
.LBB0_813:
	s_or_b64 exec, exec, s[18:19]
	s_waitcnt lgkmcnt(0)
	s_barrier
	ds_read_b128 v[34:37], v12 offset:12160
	ds_read_b128 v[38:41], v12 offset:12176
	s_and_b32 s15, s23, 7
	s_waitcnt lgkmcnt(1)
	v_add_f32_e32 v2, 0, v34
	v_add_f32_e32 v2, v2, v35
	v_add_f32_e32 v2, v2, v36
	v_add_f32_e32 v2, v2, v37
	s_waitcnt lgkmcnt(0)
	v_add_f32_e32 v2, v2, v38
	v_add_f32_e32 v2, v2, v39
	v_add_f32_e32 v2, v2, v40
	v_add_f32_e32 v2, v2, v41
	v_fmamk_f32 v2, v2, 0x3a800000, v231
	v_cmp_gt_f32_e32 vcc, s33, v2
	v_mul_f32_e32 v3, 0x4b800000, v2
	s_nop 0
	v_cndmask_b32_e32 v2, v2, v3, vcc
	v_rsq_f32_e32 v2, v2
	s_nop 0
	v_mul_f32_e32 v3, 0x45800000, v2
	v_cndmask_b32_e32 v2, v2, v3, vcc
	v_mul_f32_e32 v1, v1, v2
	v_mul_f32_e32 v0, v0, v2
	s_waitcnt vmcnt(0)
	v_mul_f32_e32 v1, v224, v1
	v_mul_f32_e32 v0, v225, v0
	ds_write2st64_b32 v22, v1, v0 offset1:8
	s_waitcnt lgkmcnt(0)
	s_barrier
	s_and_saveexec_b64 s[18:19], s[40:41]
	s_cbranch_execz .LBB0_825
	v_mov_b32_e32 v3, 0
	v_mov_b32_e32 v2, 0
	v_mov_b32_e32 v1, 0
	v_mov_b32_e32 v0, 0
	s_and_saveexec_b64 s[26:27], s[42:43]
	s_cbranch_execz .LBB0_824
	v_mov_b32_e32 v13, v12
	s_mul_i32 s0, s15, 0x180
	v_mov_b32_e32 v14, v12
	v_mov_b32_e32 v15, v12
	v_mov_b64_e32 v[0:1], v[12:13]
	v_lshl_add_u64 v[10:11], v[6:7], 0, s[0:1]
	v_mov_b64_e32 v[2:3], v[14:15]
	v_mov_b32_e32 v13, v23
	s_and_saveexec_b64 s[30:31], s[46:47]
	s_cbranch_execz .LBB0_819
	v_mov_b32_e32 v0, 0
	s_mov_b64 s[36:37], 0
	v_mov_b32_e32 v13, v26
	v_mov_b32_e32 v14, v27
	v_mov_b32_e32 v1, v0
	v_mov_b32_e32 v2, v0
	v_mov_b32_e32 v3, v0
